# P9 epilogue: the 12 residual + row-statistic loads of each half issued together (were four dependent round trips per half)
# speedup vs baseline: 1.0060x; 1.0060x over previous
.LBB0_1229:
	s_lshl_b32 s0, s16, 8
	v_mov_b32_e32 v128, v228
	v_mov_b32_e32 v130, v205
	s_or_b32 s0, s0, s54
	v_and_b32_e32 v132, 64, v197
	v_lshl_add_u32 v170, v130, 3, s0
	s_lshl_b32 s0, s20, 8
	s_add_i32 s0, s0, s51
	v_xor_b32_e32 v131, 16, v197
	v_add_u32_e32 v132, 64, v132
	v_add_u32_e32 v172, s0, v128
	v_ashrrev_i32_e32 v171, 31, v170
	v_cmp_lt_i32_e32 vcc, v131, v132
	v_lshlrev_b32_e32 v128, 2, v130
	v_lshlrev_b64 v[220:221], 1, v[170:171]
	v_cndmask_b32_e32 v131, v197, v131, vcc
	v_ashrrev_i32_e32 v173, 31, v172
	v_ashrrev_i32_e32 v129, 31, v128
	v_lshlrev_b32_e32 v232, 2, v131
	v_xor_b32_e32 v131, 32, v197
	v_lshl_add_u64 v[176:177], s[36:37], 0, v[220:221]
	v_lshlrev_b64 v[222:223], 11, v[172:173]
	v_cmp_lt_i32_e32 vcc, v131, v132
	v_lshl_add_u64 v[174:175], v[128:129], 2, s[70:71]
	v_lshl_add_u64 v[128:129], v[176:177], 0, v[222:223]
	v_lshlrev_b64 v[190:191], 6, v[172:173]
	v_cndmask_b32_e32 v131, v197, v131, vcc
	global_load_dwordx4 v[156:159], v[128:129], off
	global_load_dwordx4 v[152:155], v[128:129], off offset:256
	v_lshl_add_u64 v[128:129], v[174:175], 0, v[190:191]
	v_lshlrev_b32_e32 v231, 2, v131
	v_cmp_eq_u32_e32 vcc, 0, v130
	global_load_dwordx4 v[128:131], v[128:129], off
	v_add_u32_e32 v180, 48, v172
	v_ashrrev_i32_e32 v181, 31, v180
	v_lshlrev_b64 v[178:179], 11, v[180:181]
	v_lshlrev_b64 v[180:181], 6, v[180:181]
	v_lshl_add_u64 v[198:199], v[174:175], 0, v[180:181]
	s_lshl_b32 s24, s16, 2
	s_ashr_i32 s25, s24, 31
	v_add_u32_e32 v160, 0x30, v172
	v_ashrrev_i32_e32 v161, 31, v160
	v_lshlrev_b64 v[162:163], 11, v[160:161]
	v_lshl_add_u64 v[162:163], v[176:177], 0, v[162:163]
	global_load_dwordx4 v[164:167], v[162:163], off
	global_load_dwordx4 v[246:249], v[162:163], off offset:256
	global_load_dwordx4 v[198:201], v[198:199], off
	v_add_u32_e32 v160, 0x10, v172
	v_ashrrev_i32_e32 v161, 31, v160
	v_lshlrev_b64 v[162:163], 11, v[160:161]
	v_lshl_add_u64 v[162:163], v[176:177], 0, v[162:163]
	global_load_dwordx4 v[144:147], v[162:163], off
	global_load_dwordx4 v[136:139], v[162:163], off offset:256
	v_lshlrev_b64 v[224:225], 6, v[160:161]
	v_lshl_add_u64 v[224:225], v[174:175], 0, v[224:225]
	global_load_dwordx4 v[224:227], v[224:225], off
	v_add_u32_e32 v160, 0x20, v172
	v_ashrrev_i32_e32 v161, 31, v160
	v_lshlrev_b64 v[162:163], 11, v[160:161]
	v_lshl_add_u64 v[162:163], v[176:177], 0, v[162:163]
	global_load_dwordx4 v[148:151], v[162:163], off
	global_load_dwordx4 v[140:143], v[162:163], off offset:256
	v_lshlrev_b64 v[160:161], 6, v[160:161]
	v_lshl_add_u64 v[160:161], v[174:175], 0, v[160:161]
	global_load_dwordx4 v[160:163], v[160:161], off
	s_waitcnt vmcnt(0)
	v_mov_b32_e32 v132, v129
	v_mov_b32_e32 v133, v130
	v_mov_b32_e32 v129, v131
	v_pk_add_f32 v[132:133], v[132:133], v[128:129]
	v_add_u32_e32 v128, 16, v172
	v_ashrrev_i32_e32 v129, 31, v128
	v_lshlrev_b64 v[182:183], 11, v[128:129]
	v_lshlrev_b64 v[186:187], 6, v[128:129]
	v_lshl_add_u64 v[130:131], v[176:177], 0, v[182:183]
	v_lshl_add_u64 v[128:129], v[174:175], 0, v[186:187]
	s_nop 0
	v_mov_b32_e32 v128, v224
	v_mov_b32_e32 v129, v225
	v_mov_b32_e32 v130, v226
	v_mov_b32_e32 v131, v227
	v_mov_b32_e32 v134, v129
	v_mov_b32_e32 v135, v130
	v_mov_b32_e32 v129, v131
	v_pk_add_f32 v[128:129], v[134:135], v[128:129]
	v_mov_b32_e32 v131, v132
	v_mov_b32_e32 v130, v128
	v_mov_b32_e32 v132, v129
	v_pk_add_f32 v[128:129], v[130:131], v[132:133]
	ds_bpermute_b32 v131, v232, v129
	ds_bpermute_b32 v130, v232, v128
	s_waitcnt lgkmcnt(0)
	v_pk_add_f32 v[128:129], v[128:129], v[130:131]
	ds_bpermute_b32 v131, v231, v129
	ds_bpermute_b32 v130, v231, v128
	s_waitcnt lgkmcnt(0)
	v_pk_add_f32 v[128:129], v[128:129], v[130:131]
	s_nop 0
	v_pk_fma_f32 v[218:219], v[128:129], s[66:67], v[196:197] op_sel_hi:[1,0,0]
	s_nop 0
	v_mul_f32_e32 v128, 0x4b800000, v219
	v_cmp_gt_f32_e64 s[10:11], s80, v219
	v_cmp_gt_f32_e64 s[0:1], s80, v218
	s_nop 0
	v_cndmask_b32_e64 v128, v219, v128, s[10:11]
	v_rsq_f32_e32 v128, v128
	s_nop 0
	v_mul_f32_e32 v129, 0x45800000, v128
	v_cndmask_b32_e64 v128, v128, v129, s[10:11]
	v_mul_f32_e32 v202, v128, v128
	v_add_u32_e32 v128, 32, v172
	v_ashrrev_i32_e32 v129, 31, v128
	v_lshlrev_b64 v[184:185], 11, v[128:129]
	v_lshlrev_b64 v[188:189], 6, v[128:129]
	v_lshl_add_u64 v[130:131], v[176:177], 0, v[184:185]
	v_lshl_add_u64 v[128:129], v[174:175], 0, v[188:189]
	s_nop 0
	v_mov_b32_e32 v128, v160
	v_mov_b32_e32 v129, v161
	v_mov_b32_e32 v130, v162
	v_mov_b32_e32 v131, v163
	v_mov_b32_e32 v132, v129
	v_mov_b32_e32 v133, v130
	v_mov_b32_e32 v129, v131
	v_pk_add_f32 v[224:225], v[132:133], v[128:129]
	v_lshl_add_u64 v[128:129], v[176:177], 0, v[178:179]
	v_mov_b32_e32 v132, v164
	v_mov_b32_e32 v133, v165
	v_mov_b32_e32 v134, v166
	v_mov_b32_e32 v135, v167
	s_nop 0
	v_mov_b32_e32 v128, v246
	v_mov_b32_e32 v129, v247
	v_mov_b32_e32 v130, v248
	v_mov_b32_e32 v131, v249
	s_nop 0
	v_mov_b32_e32 v226, v199
	v_mov_b32_e32 v227, v200
	v_mov_b32_e32 v199, v201
	v_pk_add_f32 v[198:199], v[226:227], v[198:199]
	v_mov_b32_e32 v201, v224
	v_mov_b32_e32 v200, v198
	v_mov_b32_e32 v224, v199
	v_pk_add_f32 v[198:199], v[200:201], v[224:225]
	ds_bpermute_b32 v201, v232, v199
	ds_bpermute_b32 v200, v232, v198
	s_waitcnt lgkmcnt(0)
	v_pk_add_f32 v[224:225], v[198:199], v[200:201]
	v_lshlrev_b32_e32 v198, 16, v156
	v_and_b32_e32 v199, 0xffff0000, v156
	v_lshlrev_b32_e32 v156, 16, v157
	v_and_b32_e32 v157, 0xffff0000, v157
	v_lshlrev_b32_e32 v200, 16, v158
	v_and_b32_e32 v201, 0xffff0000, v158
	v_lshlrev_b32_e32 v158, 16, v159
	v_and_b32_e32 v159, 0xffff0000, v159
	v_pk_fma_f32 v[126:127], v[126:127], v[202:203], v[156:157] op_sel_hi:[1,0,1]
	v_pk_fma_f32 v[124:125], v[124:125], v[202:203], v[198:199] op_sel_hi:[1,0,1]
	v_pk_fma_f32 v[156:157], v[122:123], v[202:203], v[158:159] op_sel_hi:[1,0,1]
	v_pk_fma_f32 v[158:159], v[120:121], v[202:203], v[200:201] op_sel_hi:[1,0,1]
	v_lshl_add_u64 v[198:199], s[36:37], 0, v[222:223]
	v_cvt_pk_bf16_f32 v120, v124, v125
	v_cvt_pk_bf16_f32 v121, v126, v127
	v_cvt_pk_bf16_f32 v122, v158, v159
	v_cvt_pk_bf16_f32 v123, v156, v157
	v_lshl_add_u64 v[198:199], v[198:199], 0, v[220:221]
	global_store_dwordx4 v[198:199], v[120:123], off
	ds_bpermute_b32 v227, v231, v225
	ds_bpermute_b32 v226, v231, v224
	v_mul_f32_e32 v120, v125, v125
	v_mul_f32_e32 v121, v127, v127
	v_fmac_f32_e32 v120, v124, v124
	v_fmac_f32_e32 v121, v126, v126
	v_add_f32_e32 v120, v120, v121
	v_mul_f32_e32 v121, v159, v159
	v_fmac_f32_e32 v121, v158, v158
	v_add_f32_e32 v120, v121, v120
	v_mul_f32_e32 v121, v157, v157
	v_fmac_f32_e32 v121, v156, v156
	v_add_f32_e32 v156, v121, v120
	v_lshlrev_b32_e32 v120, 16, v152
	v_and_b32_e32 v121, 0xffff0000, v152
	v_lshlrev_b32_e32 v122, 16, v153
	v_and_b32_e32 v123, 0xffff0000, v153
	v_lshlrev_b32_e32 v124, 16, v154
	v_and_b32_e32 v125, 0xffff0000, v154
	v_lshlrev_b32_e32 v126, 16, v155
	v_and_b32_e32 v127, 0xffff0000, v155
	v_pk_fma_f32 v[118:119], v[118:119], v[202:203], v[122:123] op_sel_hi:[1,0,1]
	v_pk_fma_f32 v[116:117], v[116:117], v[202:203], v[120:121] op_sel_hi:[1,0,1]
	v_pk_fma_f32 v[120:121], v[114:115], v[202:203], v[126:127] op_sel_hi:[1,0,1]
	v_pk_fma_f32 v[122:123], v[112:113], v[202:203], v[124:125] op_sel_hi:[1,0,1]
	v_cvt_pk_bf16_f32 v112, v116, v117
	v_cvt_pk_bf16_f32 v113, v118, v119
	v_cvt_pk_bf16_f32 v114, v122, v123
	v_cvt_pk_bf16_f32 v115, v120, v121
	global_store_dwordx4 v[198:199], v[112:115], off offset:256
	s_nop 1
	v_mul_f32_e32 v112, v117, v117
	v_mul_f32_e32 v113, v119, v119
	v_fmac_f32_e32 v112, v116, v116
	v_fmac_f32_e32 v113, v118, v118
	v_add_f32_e32 v112, v112, v113
	v_mul_f32_e32 v113, v123, v123
	v_fmac_f32_e32 v113, v122, v122
	v_add_f32_e32 v112, v113, v112
	v_mul_f32_e32 v113, v121, v121
	v_fmac_f32_e32 v113, v120, v120
	v_add_f32_e32 v112, v113, v112
	v_add_f32_e32 v112, v156, v112
	ds_bpermute_b32 v113, v232, v112
	s_waitcnt lgkmcnt(0)
	v_add_f32_e32 v112, v112, v113
	ds_bpermute_b32 v113, v231, v112
	s_and_saveexec_b64 s[10:11], vcc
	s_cbranch_execz .LBB0_1231
	v_lshl_add_u64 v[114:115], s[12:13], 0, v[190:191]
	v_lshl_add_u64 v[114:115], s[24:25], 2, v[114:115]
	s_lshl_b32 s92, s49, 2
	v_lshl_add_u64 v[114:115], v[114:115], 0, s[92:93]
	s_waitcnt lgkmcnt(0)
	v_add_f32_e32 v112, v112, v113
	global_store_dword v[114:115], v112, off

.LBB0_1237:
	s_or_b64 exec, exec, s[0:1]
	v_add_u32_e32 v64, 0x80, v172
	s_waitcnt lgkmcnt(0)
	v_ashrrev_i32_e32 v65, 31, v64
	v_lshlrev_b64 v[118:119], 11, v[64:65]
	v_lshlrev_b64 v[108:109], 6, v[64:65]
	v_lshl_add_u64 v[66:67], v[176:177], 0, v[118:119]
	v_lshl_add_u64 v[64:65], v[174:175], 0, v[108:109]
	global_load_dwordx4 v[92:95], v[66:67], off
	global_load_dwordx4 v[88:91], v[66:67], off offset:256
	v_add_u32_e32 v98, 0xb0, v172
	global_load_dwordx4 v[64:67], v[64:65], off
	v_ashrrev_i32_e32 v99, 31, v98
	v_lshlrev_b64 v[96:97], 11, v[98:99]
	v_lshlrev_b64 v[98:99], 6, v[98:99]
	v_lshl_add_u64 v[114:115], v[174:175], 0, v[98:99]
	v_add_u32_e32 v132, 0xb0, v172
	v_ashrrev_i32_e32 v133, 31, v132
	v_lshlrev_b64 v[134:135], 11, v[132:133]
	v_lshl_add_u64 v[134:135], v[176:177], 0, v[134:135]
	global_load_dwordx4 v[136:139], v[134:135], off
	global_load_dwordx4 v[140:143], v[134:135], off offset:256
	global_load_dwordx4 v[114:117], v[114:115], off
	v_add_u32_e32 v132, 0x90, v172
	v_ashrrev_i32_e32 v133, 31, v132
	v_lshlrev_b64 v[134:135], 11, v[132:133]
	v_lshl_add_u64 v[134:135], v[176:177], 0, v[134:135]
	global_load_dwordx4 v[80:83], v[134:135], off
	global_load_dwordx4 v[72:75], v[134:135], off offset:256
	v_lshlrev_b64 v[128:129], 6, v[132:133]
	v_lshl_add_u64 v[128:129], v[174:175], 0, v[128:129]
	global_load_dwordx4 v[128:131], v[128:129], off
	v_add_u32_e32 v132, 0xa0, v172
	v_ashrrev_i32_e32 v133, 31, v132
	v_lshlrev_b64 v[134:135], 11, v[132:133]
	v_lshl_add_u64 v[134:135], v[176:177], 0, v[134:135]
	global_load_dwordx4 v[84:87], v[134:135], off
	global_load_dwordx4 v[76:79], v[134:135], off offset:256
	v_lshlrev_b64 v[132:133], 6, v[132:133]
	v_lshl_add_u64 v[132:133], v[174:175], 0, v[132:133]
	global_load_dwordx4 v[132:135], v[132:133], off
	s_waitcnt vmcnt(0)
	v_mov_b32_e32 v68, v65
	v_mov_b32_e32 v69, v66
	v_mov_b32_e32 v65, v67
	v_pk_add_f32 v[68:69], v[68:69], v[64:65]
	v_add_u32_e32 v64, 0x90, v172
	v_ashrrev_i32_e32 v65, 31, v64
	v_lshlrev_b64 v[100:101], 11, v[64:65]
	v_lshlrev_b64 v[104:105], 6, v[64:65]
	v_lshl_add_u64 v[66:67], v[176:177], 0, v[100:101]
	v_lshl_add_u64 v[64:65], v[174:175], 0, v[104:105]
	s_nop 0
	v_mov_b32_e32 v64, v128
	v_mov_b32_e32 v65, v129
	v_mov_b32_e32 v66, v130
	v_mov_b32_e32 v67, v131
	v_mov_b32_e32 v70, v65
	v_mov_b32_e32 v71, v66
	v_mov_b32_e32 v65, v67
	v_pk_add_f32 v[64:65], v[70:71], v[64:65]
	v_mov_b32_e32 v67, v68
	v_mov_b32_e32 v66, v64
	v_mov_b32_e32 v68, v65
	v_pk_add_f32 v[64:65], v[66:67], v[68:69]
	ds_bpermute_b32 v67, v232, v65
	ds_bpermute_b32 v66, v232, v64
	s_waitcnt lgkmcnt(0)
	v_pk_add_f32 v[64:65], v[64:65], v[66:67]
	ds_bpermute_b32 v67, v231, v65
	ds_bpermute_b32 v66, v231, v64
	s_waitcnt lgkmcnt(0)
	v_pk_add_f32 v[64:65], v[64:65], v[66:67]
	s_nop 0
	v_pk_fma_f32 v[110:111], v[64:65], s[66:67], v[196:197] op_sel_hi:[1,0,0]
	s_nop 0
	v_mul_f32_e32 v64, 0x4b800000, v111
	v_cmp_gt_f32_e64 s[10:11], s80, v111
	v_cmp_gt_f32_e64 s[0:1], s80, v110
	s_nop 0
	v_cndmask_b32_e64 v64, v111, v64, s[10:11]
	v_rsq_f32_e32 v64, v64
	s_nop 0
	v_mul_f32_e32 v65, 0x45800000, v64
	v_cndmask_b32_e64 v64, v64, v65, s[10:11]
	v_mul_f32_e32 v112, v64, v64
	v_add_u32_e32 v64, 0xa0, v172
	v_ashrrev_i32_e32 v65, 31, v64
	v_lshlrev_b64 v[102:103], 11, v[64:65]
	v_lshlrev_b64 v[106:107], 6, v[64:65]
	v_lshl_add_u64 v[66:67], v[176:177], 0, v[102:103]
	v_lshl_add_u64 v[64:65], v[174:175], 0, v[106:107]
	s_nop 0
	v_mov_b32_e32 v64, v132
	v_mov_b32_e32 v65, v133
	v_mov_b32_e32 v66, v134
	v_mov_b32_e32 v67, v135
	v_mov_b32_e32 v68, v65
	v_mov_b32_e32 v69, v66
	v_mov_b32_e32 v65, v67
	v_pk_add_f32 v[120:121], v[68:69], v[64:65]
	v_lshl_add_u64 v[64:65], v[176:177], 0, v[96:97]
	v_mov_b32_e32 v68, v136
	v_mov_b32_e32 v69, v137
	v_mov_b32_e32 v70, v138
	v_mov_b32_e32 v71, v139
	s_nop 0
	v_mov_b32_e32 v64, v140
	v_mov_b32_e32 v65, v141
	v_mov_b32_e32 v66, v142
	v_mov_b32_e32 v67, v143
	s_nop 0
	v_mov_b32_e32 v122, v115
	v_mov_b32_e32 v123, v116
	v_mov_b32_e32 v115, v117
	v_pk_add_f32 v[114:115], v[122:123], v[114:115]
	v_mov_b32_e32 v117, v120
	v_mov_b32_e32 v116, v114
	v_mov_b32_e32 v120, v115
	v_pk_add_f32 v[114:115], v[116:117], v[120:121]
	v_lshlrev_b32_e32 v120, 16, v92
	v_and_b32_e32 v121, 0xffff0000, v92
	v_lshlrev_b32_e32 v92, 16, v93
	v_and_b32_e32 v93, 0xffff0000, v93
	v_lshlrev_b32_e32 v122, 16, v94
	v_and_b32_e32 v123, 0xffff0000, v94
	v_lshlrev_b32_e32 v94, 16, v95
	v_and_b32_e32 v95, 0xffff0000, v95
	v_pk_fma_f32 v[62:63], v[62:63], v[112:113], v[92:93] op_sel_hi:[1,0,1]
	v_pk_fma_f32 v[92:93], v[60:61], v[112:113], v[120:121] op_sel_hi:[1,0,1]
	v_pk_fma_f32 v[94:95], v[58:59], v[112:113], v[94:95] op_sel_hi:[1,0,1]
	v_pk_fma_f32 v[120:121], v[56:57], v[112:113], v[122:123] op_sel_hi:[1,0,1]
	v_lshl_add_u64 v[56:57], s[36:37], 0, v[118:119]
	v_cvt_pk_bf16_f32 v58, v92, v93
	v_cvt_pk_bf16_f32 v59, v62, v63
	v_cvt_pk_bf16_f32 v60, v120, v121
	v_cvt_pk_bf16_f32 v61, v94, v95
	v_lshl_add_u64 v[56:57], v[170:171], 1, v[56:57]
	global_store_dwordx4 v[56:57], v[58:61], off
	ds_bpermute_b32 v117, v232, v115
	ds_bpermute_b32 v116, v232, v114
	v_mul_f32_e32 v58, v93, v93
	v_mul_f32_e32 v59, v63, v63
	v_fmac_f32_e32 v58, v92, v92
	v_fmac_f32_e32 v59, v62, v62
	v_add_f32_e32 v58, v58, v59
	v_mul_f32_e32 v59, v121, v121
	v_fmac_f32_e32 v59, v120, v120
	v_add_f32_e32 v58, v59, v58
	v_mul_f32_e32 v59, v95, v95
	v_fmac_f32_e32 v59, v94, v94
	v_add_f32_e32 v92, v59, v58
	v_lshlrev_b32_e32 v58, 16, v88
	v_and_b32_e32 v59, 0xffff0000, v88
	v_lshlrev_b32_e32 v60, 16, v89
	v_and_b32_e32 v61, 0xffff0000, v89
	v_lshlrev_b32_e32 v62, 16, v90
	v_and_b32_e32 v63, 0xffff0000, v90
	v_lshlrev_b32_e32 v88, 16, v91
	v_and_b32_e32 v89, 0xffff0000, v91
	v_pk_fma_f32 v[54:55], v[54:55], v[112:113], v[60:61] op_sel_hi:[1,0,1]
	v_pk_fma_f32 v[52:53], v[52:53], v[112:113], v[58:59] op_sel_hi:[1,0,1]
	v_pk_fma_f32 v[58:59], v[50:51], v[112:113], v[88:89] op_sel_hi:[1,0,1]
	v_pk_fma_f32 v[60:61], v[48:49], v[112:113], v[62:63] op_sel_hi:[1,0,1]
	v_cvt_pk_bf16_f32 v48, v52, v53
	v_cvt_pk_bf16_f32 v49, v54, v55
	v_cvt_pk_bf16_f32 v50, v60, v61
	v_cvt_pk_bf16_f32 v51, v58, v59
	global_store_dwordx4 v[56:57], v[48:51], off offset:256
	s_waitcnt lgkmcnt(0)
	v_pk_add_f32 v[114:115], v[114:115], v[116:117]
	ds_bpermute_b32 v117, v231, v115
	v_mul_f32_e32 v48, v53, v53
	v_mul_f32_e32 v49, v55, v55
	v_fmac_f32_e32 v48, v52, v52
	v_fmac_f32_e32 v49, v54, v54
	v_add_f32_e32 v48, v48, v49
	v_mul_f32_e32 v49, v61, v61
	v_fmac_f32_e32 v49, v60, v60
	v_add_f32_e32 v48, v49, v48
	v_mul_f32_e32 v49, v59, v59
	v_fmac_f32_e32 v49, v58, v58
	v_add_f32_e32 v48, v49, v48
	v_add_f32_e32 v48, v92, v48
	ds_bpermute_b32 v49, v232, v48
	ds_bpermute_b32 v116, v231, v114
	s_waitcnt lgkmcnt(1)
	v_add_f32_e32 v48, v48, v49
	ds_bpermute_b32 v49, v231, v48
	s_and_saveexec_b64 s[10:11], vcc
	s_cbranch_execz .LBB0_1239
	v_lshl_add_u64 v[50:51], s[12:13], 0, v[108:109]
	v_lshl_add_u64 v[50:51], s[24:25], 2, v[50:51]
	s_lshl_b32 s92, s49, 2
	v_lshl_add_u64 v[50:51], v[50:51], 0, s[92:93]
	s_waitcnt lgkmcnt(0)
	v_add_f32_e32 v48, v48, v49
	global_store_dword v[50:51], v48, off
